# grid barrier: one workgroup per XCD (ids 248..255) starts the L2 write-back when it arrives, ahead of the last arriver's protocol write-back
# speedup vs baseline: 1.0018x; 1.0016x over previous
.LBB0_83:
	s_lshl_b32 s3, s3, 8
	s_mov_b64 s[10:11], exec
	s_add_u32 s3, s6, s3
	s_addc_u32 s9, s7, 0
	v_mbcnt_lo_u32_b32 v1, s10, 0
	s_add_u32 s8, s3, 0x1000
	v_mbcnt_hi_u32_b32 v1, s11, v1
	s_addc_u32 s9, s9, 0
	v_cmp_eq_u32_e32 vcc, 0, v1
	s_and_saveexec_b64 s[12:13], vcc
	s_cbranch_execz .LBB0_85
	s_bcnt1_i32_b64 s3, s[10:11]
	v_mov_b32_e32 v3, 0x1000
	v_mov_b32_e32 v4, s3
	v_readlane_b32 s98, v254, 35
	s_cmpk_lt_u32 s98, 0xf8
	s_cbranch_scc1 .Lewb_0
	buffer_wbl2 sc1
.Lewb_0:
	global_atomic_add v3, v3, v4, s[8:9] offset:1024 sc0

.LBB0_160:
	s_lshl_b32 s8, s50, 8
	s_mov_b64 s[12:13], exec
	s_add_u32 s8, s6, s8
	s_addc_u32 s9, s7, 0
	v_mbcnt_lo_u32_b32 v1, s12, 0
	s_add_u32 s8, s8, 0x1000
	v_mbcnt_hi_u32_b32 v1, s13, v1
	s_addc_u32 s9, s9, 0
	v_cmp_eq_u32_e32 vcc, 0, v1
	s_and_saveexec_b64 s[14:15], vcc
	s_cbranch_execz .LBB0_162
	s_bcnt1_i32_b64 s12, s[12:13]
	v_mov_b32_e32 v3, s12
	v_mov_b32_e32 v4, 0x1000
	v_readlane_b32 s98, v254, 35
	s_cmpk_lt_u32 s98, 0xf8
	s_cbranch_scc1 .Lewb_1
	buffer_wbl2 sc1
.Lewb_1:
	global_atomic_add v3, v4, v3, s[8:9] offset:1024 sc0

.LBB0_237:
	s_lshl_b32 s4, s4, 8
	s_mov_b64 s[18:19], exec
	s_add_u32 s4, s8, s4
	s_addc_u32 s5, s9, 0
	v_mbcnt_lo_u32_b32 v1, s18, 0
	s_add_u32 s16, s4, 0x1000
	v_mbcnt_hi_u32_b32 v1, s19, v1
	s_addc_u32 s17, s5, 0
	v_cmp_eq_u32_e32 vcc, 0, v1
	s_and_saveexec_b64 s[20:21], vcc
	s_cbranch_execz .LBB0_239
	s_bcnt1_i32_b64 s4, s[18:19]
	v_mov_b32_e32 v3, s4
	v_mov_b32_e32 v4, 0x1000
	v_readlane_b32 s98, v254, 35
	s_cmpk_lt_u32 s98, 0xf8
	s_cbranch_scc1 .Lewb_2
	buffer_wbl2 sc1
.Lewb_2:
	global_atomic_add v3, v4, v3, s[16:17] offset:1024 sc0

.LBB0_310:
	s_lshl_b32 s4, s4, 8
	s_mov_b64 s[12:13], exec
	s_add_u32 s4, s8, s4
	s_addc_u32 s5, s9, 0
	v_mbcnt_lo_u32_b32 v1, s12, 0
	s_add_u32 s10, s4, 0x1000
	v_mbcnt_hi_u32_b32 v1, s13, v1
	s_addc_u32 s11, s5, 0
	v_cmp_eq_u32_e32 vcc, 0, v1
	s_and_saveexec_b64 s[14:15], vcc
	s_cbranch_execz .LBB0_312
	s_bcnt1_i32_b64 s4, s[12:13]
	v_mov_b32_e32 v3, s4
	v_mov_b32_e32 v4, 0x1000
	v_readlane_b32 s98, v254, 35
	s_cmpk_lt_u32 s98, 0xf8
	s_cbranch_scc1 .Lewb_3
	buffer_wbl2 sc1
.Lewb_3:
	global_atomic_add v3, v4, v3, s[10:11] offset:1024 sc0

.LBB0_707:
	s_lshl_b32 s8, s50, 8
	s_mov_b64 s[10:11], exec
	s_add_u32 s8, s6, s8
	s_addc_u32 s9, s7, 0
	v_mbcnt_lo_u32_b32 v1, s10, 0
	s_add_u32 s8, s8, 0x1000
	v_mbcnt_hi_u32_b32 v1, s11, v1
	s_addc_u32 s9, s9, 0
	v_cmp_eq_u32_e32 vcc, 0, v1
	s_and_saveexec_b64 s[12:13], vcc
	s_cbranch_execz .LBB0_709
	s_bcnt1_i32_b64 s10, s[10:11]
	v_mov_b32_e32 v3, s10
	v_mov_b32_e32 v4, 0x1000
	v_readlane_b32 s98, v254, 35
	s_cmpk_lt_u32 s98, 0xf8
	s_cbranch_scc1 .Lewb_6
	buffer_wbl2 sc1
